# tail fill: last 32 gate units (br3 tiles 2024..2055) moved into idle blocks of gemm_in last round, gate pass = exactly 16 rounds
# baseline (speedup 1.0000x reference)
; DI int vblock() { const int G = gridDim.x; return (G & 7) ? (int)blockIdx.x : (int)((blockIdx.x & 7) * (G >> 3) + (blockIdx.x >> 3)); }
; DI void phase_merge(const Params& p, int l, LAS char* lds) {
;     ...
;     const int lane = tidx & 63, w = tidx >> 6, wm = w >> 1, wn = w & 1, fr = lane & 15, fq = lane >> 4;
;     unsigned* stash = (unsigned*)(p.ws + OFF_ZC) + tidx;
;     const int G = gridDim.x, NT = 257 * 8, vb = vblock();
;     const int ntl = (vb < NT) ? (NT - vb + G - 1) / G : 0;
;     const int nops = 8 * ntl;
;     auto op_of = [&](int f) {
;         if (f < 4 * ntl) {
;             const int br = f / ntl, i = vb + (f - br * ntl) * G, mt = i >> 3, nt = i & 7;
;             return GOp{h + (size_t)mt * 128 * 1024, W + W_IN + (size_t)(3328 + br * 1024 + nt * 128) * 1024, 1024, 1024, 1024, 2 * (mt + nt)};
;         }
;         const int f2 = f - 4 * ntl, k = f2 >> 2, br = f2 & 3, i = vb + k * G, mt = i >> 3, nt = i & 7;
;         const int koff = (br == 0) ? 0 : (br == 1) ? 256 : (br == 2) ? 768 : 1024;
;         const int kk = (br == 1) ? 512 : 256;
;         const size_t woff = (br == 0) ? W_OP : (br == 1) ? W_OM : (br == 2) ? W_OC : W_OS;
;         return GOp{u + (size_t)mt * 128 * 1280 + koff, W + woff + (size_t)nt * 128 * kk, 1280, kk, kk, mt + nt};
;     };
;     f32x4 acc[4][4];
;     bool inflight = false;
;     unsigned sq[4][4], sqn[4][4];
; #pragma unroll
;     for (int mi = 0; mi < 4; ++mi)
; #pragma unroll
;         for (int ni = 0; ni < 4; ++ni) { sq[mi][ni] = 0x01010101u; sqn[mi][ni] = 0x01010101u; }
;     for (int f = 0; f < nops; ++f) {
;         const bool gate = f < 4 * ntl;
;         int br, i;
;         if (gate) { br = f / ntl; i = vb + (f - br * ntl) * G; } else { const int f2 = f - 4 * ntl; br = f2 & 3; i = vb + (f2 >> 2) * G; }
;         const int mt = i >> 3, nt = i & 7;
;         const bool has_next = f + 1 < nops;
;         const GOp g = op_of(f), gn = op_of(has_next ? f + 1 : f);
;         unsigned* st = stash + (size_t)(i * 4 + br) * 4096;
.Lgp_entry:
	s_waitcnt vmcnt(0)
	v_mov_b32_e32 v2, v151
	v_lshlrev_b32_e32 v4, 4, v2
	v_and_b32_e32 v67, 0xfffffc00, v4
	v_lshrrev_b32_e32 v4, 4, v2
	v_xor_b32_e32 v4, v4, v2
	v_lshlrev_b32_e32 v7, 7, v2
	v_readlane_b32 s8, v228, 30
	v_and_b32_e32 v5, 48, v2
	v_and_b32_e32 v6, 0xfffffc00, v7
	v_lshlrev_b32_e32 v4, 3, v4
	v_lshlrev_b32_e32 v9, 3, v2
	s_movk_i32 s4, 0x70
	s_mul_i32 s0, s8, 0x13a0000
	v_and_b32_e32 v1, 64, v2
	v_and_b32_e32 v3, 15, v2
	v_and_or_b32 v148, v4, 56, v6
	v_bitop3_b32 v10, v9, v2, 48 bitop3:0x78
	v_bitop3_b32 v86, v9, s4, v5 bitop3:0x48
	v_ashrrev_i32_e32 v5, 1, v2
	s_movk_i32 s4, 0xffc0
	v_and_b32_e32 v66, 16, v2
	v_lshrrev_b32_e32 v2, 2, v2
	s_mul_hi_i32 s1, s8, 0x13a0000
	s_add_u32 s0, s98, s0
	v_add_u32_e32 v4, 0x8000, v148
	v_add_u32_e32 v6, 0x10000, v148
	v_add_u32_e32 v8, 0x18000, v148
	v_and_or_b32 v87, v5, s4, v3
	v_and_b32_e32 v89, 0x2780, v7
	v_mov_b32_e32 v5, v149
	v_mov_b32_e32 v7, v149
	v_mov_b32_e32 v9, v149
	v_and_b32_e32 v2, 8, v2
	s_addc_u32 s1, s99, s1
	v_lshlrev_b32_e32 v88, 7, v87
	v_bitop3_b32 v90, v10, 64, v168 bitop3:0x6c
	s_mov_b64 s[46:47], 0
	v_lshlrev_b32_e32 v68, 1, v2
	v_lshlrev_b64 v[70:71], 1, v[148:149]
	v_lshlrev_b64 v[72:73], 1, v[4:5]
	v_lshlrev_b64 v[74:75], 1, v[6:7]
	v_lshlrev_b64 v[76:77], 1, v[8:9]
	v_readlane_b32 s4, v229, 39
	v_readfirstlane_b32 s100, v67
	s_mov_b32 s56, s4
	v_lshlrev_b32_e32 v1, 2, v151
	v_and_b32_e32 v77, 64, v151
	v_lshrrev_b32_e32 v3, 2, v151
	v_and_b32_e32 v3, 12, v3
	v_or_b32_e32 v77, v77, v3
	v_lshlrev_b32_e32 v77, 2, v77
	v_readlane_b32 s60, v228, 19
	v_readlane_b32 s61, v228, 20
	v_readlane_b32 s62, v229, 53
	v_readlane_b32 s63, v229, 54
	s_lshl_b32 s5, s8, 14
	s_add_u32 s62, s62, s5
	s_addc_u32 s63, s63, 0
	s_cmpk_gt_u32 s56, 0x1fff
	s_cbranch_scc1 .Lgp_done
.Lgp_tile:
	s_mov_b32 s55, s56
	s_mov_b32 s54, 0
	s_cmp_ge_u32 s55, 0x808
	s_cselect_b32 s5, 1, 0
	s_add_u32 s54, s54, s5
	s_mul_i32 s5, s5, 0x808
	s_sub_u32 s55, s55, s5
	s_cmp_ge_u32 s55, 0x808
	s_cselect_b32 s5, 1, 0
	s_add_u32 s54, s54, s5
	s_mul_i32 s5, s5, 0x808
	s_sub_u32 s55, s55, s5
	s_cmp_ge_u32 s55, 0x808
	s_cselect_b32 s5, 1, 0
	s_add_u32 s54, s54, s5
	s_mul_i32 s5, s5, 0x808
	s_sub_u32 s55, s55, s5
	s_lshr_b32 s48, s55, 3
	s_and_b32 s5, s55, 7
	s_lshl_b32 s6, s54, 3
	s_add_u32 s50, s5, s6
	s_add_u32 s50, s50, 26
	s_add_i32 s23, s56, s22
	s_cmpk_lt_u32 s23, 0x2000
	s_cselect_b64 s[42:43], -1, 0
	s_cbranch_scc0 .Lgp_nonext
	s_mov_b32 s52, s23
	s_mov_b32 s57, 0
	s_cmp_ge_u32 s52, 0x808
	s_cselect_b32 s5, 1, 0
	s_add_u32 s57, s57, s5
	s_mul_i32 s5, s5, 0x808
	s_sub_u32 s52, s52, s5
	s_cmp_ge_u32 s52, 0x808
	s_cselect_b32 s5, 1, 0
	s_add_u32 s57, s57, s5
	s_mul_i32 s5, s5, 0x808
	s_sub_u32 s52, s52, s5
	s_cmp_ge_u32 s52, 0x808
	s_cselect_b32 s5, 1, 0
	s_add_u32 s57, s57, s5
	s_mul_i32 s5, s5, 0x808
	s_sub_u32 s52, s52, s5
	s_lshr_b32 s38, s52, 3
	s_and_b32 s5, s52, 7
	s_lshl_b32 s6, s57, 3
	s_add_u32 s44, s5, s6
	s_add_u32 s44, s44, 26

; DI void phase_merge(const Params& p, int l, LAS char* lds) {
;     ...
;         if (has_next && f + 1 >= 4 * ntl) {
;             const int f2 = f + 1 - 4 * ntl;
;             const unsigned* stn = stash + (size_t)((vb + (f2 >> 2) * G) * 4 + (f2 & 3)) * 4096;
; #pragma unroll
;             for (int mi = 0; mi < 4; ++mi)
; #pragma unroll
;                 for (int ni = 0; ni < 4; ++ni) sqn[mi][ni] = stn[(mi * 4 + ni) * 256];
.LBB0_253:
	s_cmp_lt_i32 s69, s66
	s_cselect_b64 s[4:5], -1, 0
	s_xor_b64 s[6:7], s[50:51], -1
	s_or_b64 s[4:5], s[4:5], s[6:7]
	s_and_b64 vcc, exec, s[4:5]
	s_cbranch_vccnz .LBB0_255
	s_sub_i32 s4, s69, s66
	s_lshr_b32 s4, s4, 2
	s_mul_i32 s4, s4, s22
	s_add_i32 s4, s4, s73
	s_and_b32 s5, s69, 3
	s_cmp_eq_u32 s5, 3
	s_cselect_b32 s6, 1, 0
	s_cmp_ge_u32 s4, 0x7e8
	s_cselect_b32 s7, 1, 0
	s_and_b32 s6, s6, s7
	s_cmp_eq_u32 s6, 1
	s_cbranch_scc1 .Lsq_scr
	s_lshl_b32 s4, s4, 2
	s_or_b32 s4, s4, s5
	s_ashr_i32 s5, s4, 31
	s_lshl_b64 s[4:5], s[4:5], 14
	s_branch .Lsq_adr
.Lsq_scr:
	s_sub_u32 s4, s4, 0x7e8
	s_lshl_b32 s4, s4, 14
	s_add_u32 s4, s4, 0x12260c00
	s_mov_b32 s5, 0

; #define LAS __attribute__((address_space(3)))
; DI void gload_lds16(const void* g, LAS char* l) { __builtin_amdgcn_global_load_lds((const unsigned*)g, (LAS unsigned*)l, 16, 0, 0); }
; template <bool WIDE = false>
; DI void gemm_core(f32x4 (&acc)[4][4], const GOp& g, LAS char* lds, const int tidx, const bool have_first, const bool has_next, const GOp& gn, const bool fw16 = false) {
;     ...
;     const int nk = g.K >> 6;
;     const int fr = lane & 15, fq = lane >> 4;
;     const int sw = (fq ^ (fr >> 1)) << 4;
;     const int aoff = (wm * 64 + fr) * 128, boff = 16384 + (wn * 64 + fr) * 128;
;     if (!have_first) gemm_issue(g, 0, lds, w, lane);
;     for (int kt = 0; kt < nk; ++kt) {
;         if (kt == 0 && have_first && fw16) {
;             asm volatile("s_waitcnt vmcnt(8) lgkmcnt(0)" ::: "memory");
;             __builtin_amdgcn_s_barrier();
;             asm volatile("" ::: "memory");
;         } else {
;             asm volatile("s_waitcnt vmcnt(0)" ::: "memory");
;             __syncthreads();
;         }
;         if (kt + 1 < nk) {
;             LAS char* base = lds + ((kt + 1) & 1) * 32768 + w * 1024;
;             const int kn = ((kt + 1 + g.krot) & (nk - 1)) * 64;
;             const bf16_t* Ak = g.A + kn; const bf16_t* Bk = g.Bt + kn;
; #pragma unroll
;             for (int j = 0; j < 4; ++j) { gload_lds16(Ak + oa[j], base + j * 4096); gload_lds16(Bk + ob[j], base + 16384 + j * 4096); }
;         } else if (has_next) gemm_issue(gn, 0, lds, w, lane);
; DI void phase_merge(const Params& p, int l, LAS char* lds) {
;     ...
;     auto op_of = [&](int f) {
;         if (f < 4 * ntl) {
;             const int br = f / ntl, i = vb + (f - br * ntl) * G, mt = i >> 3, nt = i & 7;
;             return GOp{h + (size_t)mt * 128 * 1024, W + W_IN + (size_t)(3328 + br * 1024 + nt * 128) * 1024, 1024, 1024, 1024, 2 * (mt + nt)};
.LBB0_402:
	v_readlane_b32 s33, v229, 39
	s_nop 0
	s_cmp_lt_u32 s33, 26
	s_cbranch_scc1 .Lgx_skip
	s_sub_u32 s33, s33, 26
	s_cmp_ge_u32 s33, 32
	s_cbranch_scc1 .Lgx_skip
	v_lshlrev_b32_e32 v1, 2, v151
	v_and_b32_e32 v77, 64, v151
	v_lshrrev_b32_e32 v3, 2, v151
	v_and_b32_e32 v3, 12, v3
	v_or_b32_e32 v77, v77, v3
	v_lshlrev_b32_e32 v77, 2, v77
	s_add_u32 s4, s33, 0x7e8
	s_lshr_b32 s48, s4, 3
	s_and_b32 s5, s4, 7
	s_add_u32 s50, s5, 50
	v_readlane_b32 s52, v229, 53
	v_readlane_b32 s53, v229, 54
	v_readlane_b32 s6, v228, 30
	s_lshl_b32 s6, s6, 14
	s_lshl_b32 s5, s5, 9
	s_add_u32 s6, s6, s5
	s_add_u32 s6, s6, 0x3000
	s_add_u32 s52, s52, s6
	s_addc_u32 s53, s53, 0
	s_lshl_b32 s4, s33, 14
	s_add_u32 s4, s4, 0x1b120c00
	s_add_u32 s40, s98, s4
	s_addc_u32 s41, s99, 0
	s_mov_b64 s[46:47], 0
	s_mov_b64 s[42:43], 0
	global_load_dword v66, v77, s[52:53] offset:0
	global_load_dword v68, v77, s[52:53] offset:4
	global_load_dword v69, v77, s[52:53] offset:8
	global_load_dword v93, v77, s[52:53] offset:12
	global_load_dword v146, v77, s[52:53] offset:64
	global_load_dword v147, v77, s[52:53] offset:68
	global_load_dword v148, v77, s[52:53] offset:72
	global_load_dword v160, v77, s[52:53] offset:76
	global_load_dword v161, v77, s[52:53] offset:128
	global_load_dword v182, v77, s[52:53] offset:132
	global_load_dword v183, v77, s[52:53] offset:136
	global_load_dword v184, v77, s[52:53] offset:140
	global_load_dword v185, v77, s[52:53] offset:192
	global_load_dword v71, v77, s[52:53] offset:196
	global_load_dword v73, v77, s[52:53] offset:200
	global_load_dword v75, v77, s[52:53] offset:204
	s_ashr_i32 s49, s48, 31
	s_lshl_b64 s[4:5], s[48:49], 18
	s_add_u32 s39, s26, s4
	s_addc_u32 s45, s27, s5
	s_ashr_i32 s51, s50, 31
	s_lshl_b64 s[4:5], s[50:51], 18
	s_add_u32 s49, s0, s4
	s_addc_u32 s51, s1, s5
	s_add_i32 s4, s50, s48
	s_lshl_b32 s48, s4, 7
	v_add_u32_e32 v226, v88, v86
	v_add_u32_e32 v227, v89, v86
	v_add_u32_e32 v91, v88, v90
	v_add_u32_e32 v92, v89, v90
	s_mov_b32 s34, s48
	s_and_b64 vcc, exec, s[46:47]
	s_cbranch_vccnz .Lgx_have
	s_and_b32 s4, s34, 0x3c0
	s_lshl_b32 s6, s4, 1
	s_add_u32 s4, s39, s6
	s_addc_u32 s5, s45, 0
	s_add_u32 s6, s49, s6
	s_addc_u32 s7, s51, 0
	s_add_i32 s34, s34, 64
	s_add_u32 m0, s100, 0x0
	s_nop 0
	global_load_lds_dwordx4 v70, s[4:5]
	s_add_u32 m0, s100, 0x4000
	s_nop 0
	global_load_lds_dwordx4 v70, s[6:7]
	s_add_u32 m0, s100, 0x1000
	s_nop 0
	global_load_lds_dwordx4 v72, s[4:5]
	s_add_u32 m0, s100, 0x5000
	s_nop 0
	global_load_lds_dwordx4 v72, s[6:7]
	s_add_u32 m0, s100, 0x2000
	s_nop 0
	global_load_lds_dwordx4 v74, s[4:5]
	s_add_u32 m0, s100, 0x6000
	s_nop 0
	global_load_lds_dwordx4 v74, s[6:7]
	s_add_u32 m0, s100, 0x3000
	s_nop 0
	global_load_lds_dwordx4 v76, s[4:5]
	s_add_u32 m0, s100, 0x7000
	s_nop 0
	global_load_lds_dwordx4 v76, s[6:7]
	s_and_b32 s4, s34, 0x3c0
	s_lshl_b32 s6, s4, 1
	s_add_u32 s4, s39, s6
	s_addc_u32 s5, s45, 0
	s_add_u32 s6, s49, s6
	s_addc_u32 s7, s51, 0
	s_add_i32 s34, s34, 64
	s_add_u32 m0, s100, 0x8000
	s_nop 0
	global_load_lds_dwordx4 v70, s[4:5]
	s_add_u32 m0, s100, 0xc000
	s_nop 0
	global_load_lds_dwordx4 v70, s[6:7]
	s_add_u32 m0, s100, 0x9000
	s_nop 0
	global_load_lds_dwordx4 v72, s[4:5]
	s_add_u32 m0, s100, 0xd000
	s_nop 0
	global_load_lds_dwordx4 v72, s[6:7]
	s_add_u32 m0, s100, 0xa000
	s_nop 0
	global_load_lds_dwordx4 v74, s[4:5]
	s_add_u32 m0, s100, 0xe000
	s_nop 0
	global_load_lds_dwordx4 v74, s[6:7]
	s_add_u32 m0, s100, 0xb000
	s_nop 0
	global_load_lds_dwordx4 v76, s[4:5]
	s_add_u32 m0, s100, 0xf000
	s_nop 0
	global_load_lds_dwordx4 v76, s[6:7]
	s_waitcnt vmcnt(8)
	s_barrier
	ds_read_b128 v[94:97], v226 offset:0
	ds_read_b128 v[98:101], v226 offset:2048
	ds_read_b128 v[102:105], v226 offset:4096
	ds_read_b128 v[106:109], v226 offset:6144
	ds_read_b128 v[110:113], v227 offset:16384
	ds_read_b128 v[114:117], v227 offset:18432
	ds_read_b128 v[118:121], v227 offset:20480
	ds_read_b128 v[122:125], v227 offset:22528
	ds_read_b128 v[126:129], v91 offset:0
	ds_read_b128 v[130:133], v91 offset:2048
	ds_read_b128 v[134:137], v91 offset:4096
	ds_read_b128 v[138:141], v91 offset:6144
	ds_read_b128 v[142:145], v92 offset:16384
	ds_read_b128 v[152:155], v92 offset:18432
	ds_read_b128 v[156:159], v92 offset:20480
	ds_read_b128 v[178:181], v92 offset:22528
	s_waitcnt lgkmcnt(0)
	s_barrier
	s_and_b32 s4, s34, 0x3c0
	s_lshl_b32 s6, s4, 1
	s_add_u32 s4, s39, s6
	s_addc_u32 s5, s45, 0
	s_add_u32 s6, s49, s6
	s_addc_u32 s7, s51, 0
	s_add_i32 s34, s34, 64
	s_add_u32 m0, s100, 0x0
	s_nop 0
	global_load_lds_dwordx4 v70, s[4:5]
	s_add_u32 m0, s100, 0x4000
	s_nop 0
	global_load_lds_dwordx4 v70, s[6:7]
	s_add_u32 m0, s100, 0x1000
	s_nop 0
	global_load_lds_dwordx4 v72, s[4:5]
	s_add_u32 m0, s100, 0x5000
	s_nop 0
	global_load_lds_dwordx4 v72, s[6:7]
	s_add_u32 m0, s100, 0x2000
	s_nop 0
	global_load_lds_dwordx4 v74, s[4:5]
	s_add_u32 m0, s100, 0x6000
	s_nop 0
	global_load_lds_dwordx4 v74, s[6:7]
	s_add_u32 m0, s100, 0x3000
	s_nop 0
	global_load_lds_dwordx4 v76, s[4:5]
	s_add_u32 m0, s100, 0x7000
	s_nop 0
	global_load_lds_dwordx4 v76, s[6:7]
	s_waitcnt vmcnt(8)
	s_branch .Lgx_k0
